# P7 MLA fast loop: static s_setprio 1 for the younger half (waves 4-7) before the loop, s_setprio 0 at loop exit
# baseline (speedup 1.0000x reference)
.Lf_entry:
	v_readlane_b32 s44, v254, 3
	s_nop 0
	s_cmpk_lt_u32 s44, 0x100
	s_cbranch_scc1 .Lf_noprio
	s_setprio 1

.Lf_exit:
	s_setprio 0
	v_add_f32_e32 v248, v244, v245
	v_add_f32_e32 v248, v246, v248
	v_add_f32_e32 v248, v247, v248
	v_add_f32_e32 v248, v241, v248
	v_add_f32_e32 v206, v206, v248
	v_add_f32_e32 v248, v250, v251
	v_add_f32_e32 v248, v252, v248
	v_add_f32_e32 v248, v253, v248
	v_add_f32_e32 v248, v240, v248
	v_add_f32_e32 v0, v0, v248
